# FoX near-diagonal tiles: K and V fragment reads batched behind counted waits
# baseline (speedup 1.0000x reference)
; #define LAS __attribute__((address_space(3)))
; template <int MODE>
; __device__ __forceinline__ void attn_item(const AttnP& p, int b, int h, int qb, LAS unsigned char* lds) {
;     ...
;                     if (MODE == 0) {
;                         const LAS float* tab = (const LAS float*)(lds + TAB_OFF);
;                         if (qw - (kp0 + 31) >= 128) {
;                             const float cb = tab[255] - mfix;
; #pragma unroll
;                             for (int c = 0; c < NC; ++c) { ATT_QK(c, cb); ATT_TAIL(c); }
;                         } else {
;                             float binit[16];
; #pragma unroll
;                             for (int i = 0; i < 16; ++i) {
;                                 const int dist = qrow - (kp0 + crow(i, hh));
;                                 binit[i] = (dist < 0) ? -3e38f : (tab[dist > 255 ? 255 : dist] - mfix);
;                             }
; #pragma unroll
;                             for (int c = 0; c < NC; ++c) { ATT_QK(c, binit[i]); ATT_TAIL(c); }
;                         }
;                     } else {
;                         float binit[16];
;                         const LAS float* bl = (const LAS float*)(vtb + VT_BYTES) + 32 * kb2 + 4 * hh;
; #pragma unroll
;                         for (int g = 0; g < 4; ++g) {
;                             const f32x4 t = *(const LAS f32x4*)(bl + 8 * g);
; #pragma unroll
;                             for (int e = 0; e < 4; ++e) binit[4 * g + e] = (need_mask && (kp0 + crow(4 * g + e, hh) > qrow)) ? -3e38f : (t[e] - mfix);
;                         }
;                         ATT_QK(0, binit[i]); ATT_TAIL(0);
;                     }
;     ...
;                 }
; #pragma unroll
;                 for (int t2 = 0; t2 < 2; ++t2)
; #pragma unroll
;                     for (int d = 0; d < DV / 32; ++d) {
;                         const LAS unsigned char* vp = vtb + ((32 * kb2 + 16 * t2 + 4 * hh + ((lane & 15) >> 2)) * VPT + d * 32 + 16 * ((lane >> 4) & 1) + 4 * (lane & 3)) * 2;
;                         const s16x4 lo = vtr(vp), hi = vtr(vp + 8 * VPT * 2);
;                         const bf16x8 va = __builtin_shufflevector(lo, hi, 0, 1, 2, 3, 4, 5, 6, 7);
; #pragma unroll
;                         for (int c = 0; c < NC; ++c) O[c][d] = MFMA32(va, pb[c][t2], O[c][d]);
;                     }
.LBB0_235:
	ds_read_b128 v[2:5], v8 offset:21632
	ds_read_b128 v[10:13], v8 offset:21664
	s_cmp_gt_i32 s33, s27
	v_subrev_u32_e32 v9, 31, v7
	s_cselect_b64 s[24:25], -1, 0
	v_cmp_gt_i32_e32 vcc, v9, v115
	s_and_b64 vcc, s[24:25], vcc
	s_waitcnt lgkmcnt(0)
	v_sub_f32_e32 v2, v2, v121
	v_cndmask_b32_e32 v48, v2, v219, vcc
	v_cmp_ge_i32_e32 vcc, v9, v115
	s_and_b64 vcc, s[24:25], vcc
	v_sub_f32_e32 v2, v3, v121
	v_cndmask_b32_e32 v49, v2, v219, vcc
	v_subrev_u32_e32 v2, 29, v7
	v_cmp_gt_i32_e32 vcc, v2, v115
	s_and_b64 vcc, s[24:25], vcc
	v_sub_f32_e32 v2, v4, v121
	v_cndmask_b32_e32 v50, v2, v219, vcc
	v_subrev_u32_e32 v2, 28, v7
	v_cmp_gt_i32_e32 vcc, v2, v115
	s_and_b64 vcc, s[24:25], vcc
	v_sub_f32_e32 v2, v5, v121
	v_cndmask_b32_e32 v51, v2, v219, vcc
	v_subrev_u32_e32 v2, 23, v7
	v_cmp_gt_i32_e32 vcc, v2, v115
	s_and_b64 vcc, s[24:25], vcc
	v_sub_f32_e32 v2, v10, v121
	v_cndmask_b32_e32 v52, v2, v219, vcc
	v_subrev_u32_e32 v2, 22, v7
	v_cmp_gt_i32_e32 vcc, v2, v115
	s_and_b64 vcc, s[24:25], vcc
	v_sub_f32_e32 v2, v11, v121
	v_cndmask_b32_e32 v53, v2, v219, vcc
	v_subrev_u32_e32 v2, 21, v7
	v_cmp_gt_i32_e32 vcc, v2, v115
	s_and_b64 vcc, s[24:25], vcc
	v_sub_f32_e32 v2, v12, v121
	v_cndmask_b32_e32 v54, v2, v219, vcc
	v_subrev_u32_e32 v2, 20, v7
	v_cmp_gt_i32_e32 vcc, v2, v115
	s_and_b64 vcc, s[24:25], vcc
	v_sub_f32_e32 v2, v13, v121
	v_cndmask_b32_e32 v55, v2, v219, vcc
	ds_read_b128 v[2:5], v8 offset:21696
	v_add_u32_e32 v9, -15, v7
	v_cmp_gt_i32_e32 vcc, v9, v115
	s_and_b64 vcc, s[24:25], vcc
	v_add_u32_e32 v9, -7, v7
	s_waitcnt lgkmcnt(0)
	v_sub_f32_e32 v2, v2, v121
	v_cndmask_b32_e32 v56, v2, v219, vcc
	v_add_u32_e32 v2, -14, v7
	v_cmp_gt_i32_e32 vcc, v2, v115
	s_and_b64 vcc, s[24:25], vcc
	v_sub_f32_e32 v2, v3, v121
	v_cndmask_b32_e32 v57, v2, v219, vcc
	v_add_u32_e32 v2, -13, v7
	v_cmp_gt_i32_e32 vcc, v2, v115
	s_and_b64 vcc, s[24:25], vcc
	v_sub_f32_e32 v2, v4, v121
	v_cndmask_b32_e32 v58, v2, v219, vcc
	v_add_u32_e32 v2, -12, v7
	v_cmp_gt_i32_e32 vcc, v2, v115
	s_and_b64 vcc, s[24:25], vcc
	v_sub_f32_e32 v2, v5, v121
	v_cndmask_b32_e32 v59, v2, v219, vcc
	ds_read_b128 v[2:5], v8 offset:21728
	v_cmp_gt_i32_e32 vcc, v9, v115
	s_and_b64 vcc, s[24:25], vcc
	s_waitcnt lgkmcnt(0)
	v_sub_f32_e32 v2, v2, v121
	v_cndmask_b32_e32 v60, v2, v219, vcc
	v_add_u32_e32 v2, -6, v7
	v_cmp_gt_i32_e32 vcc, v2, v115
	s_and_b64 vcc, s[24:25], vcc
	v_sub_f32_e32 v2, v3, v121
	v_cndmask_b32_e32 v61, v2, v219, vcc
	v_add_u32_e32 v2, -5, v7
	v_cmp_gt_i32_e32 vcc, v2, v115
	s_and_b64 vcc, s[24:25], vcc
	v_sub_f32_e32 v2, v4, v121
	v_cndmask_b32_e32 v62, v2, v219, vcc
	v_add_u32_e32 v2, -4, v7
	v_cmp_gt_i32_e32 vcc, v2, v115
	s_and_b64 vcc, s[24:25], vcc
	v_sub_f32_e32 v2, v5, v121
	v_cndmask_b32_e32 v63, v2, v219, vcc
	ds_read_b128 v[2:5], v6 offset:4608
	ds_read_b128 v[10:13], v6 offset:4640
	ds_read_b128 v[140:143], v6 offset:4672
	ds_read_b128 v[144:147], v6 offset:4704
	s_waitcnt lgkmcnt(3)
	v_mfma_f32_32x32x16_bf16 v[48:63], v[2:5], v[72:75], v[48:63]
	s_waitcnt lgkmcnt(2)
	v_mfma_f32_32x32x16_bf16 v[48:63], v[10:13], v[76:79], v[48:63]
	s_waitcnt lgkmcnt(1)
	v_mfma_f32_32x32x16_bf16 v[48:63], v[140:143], v[80:83], v[48:63]
	s_waitcnt lgkmcnt(0)
	v_mfma_f32_32x32x16_bf16 v[48:63], v[144:147], v[84:87], v[48:63]
	s_nop 11
	v_exp_f32_e32 v2, v48
	v_exp_f32_e32 v4, v49
	v_exp_f32_e32 v5, v50
	v_exp_f32_e32 v9, v51
	v_add_f32_e32 v3, 0, v2
	v_exp_f32_e32 v12, v52
	v_add_f32_e32 v3, v4, v3
	v_exp_f32_e32 v13, v53
	v_add_f32_e32 v3, v5, v3
	v_exp_f32_e32 v14, v54
	v_add_f32_e32 v3, v9, v3
	v_exp_f32_e32 v15, v55
	v_add_f32_e32 v3, v12, v3
	v_exp_f32_e32 v48, v56
	v_add_f32_e32 v3, v13, v3
	v_exp_f32_e32 v49, v57
	v_add_f32_e32 v3, v14, v3
	v_exp_f32_e32 v50, v58
	v_add_f32_e32 v3, v15, v3
	v_exp_f32_e32 v51, v59
	v_add_f32_e32 v3, v48, v3
	v_exp_f32_e32 v52, v60
	v_add_f32_e32 v3, v49, v3
	v_exp_f32_e32 v53, v61
	v_add_f32_e32 v3, v50, v3
	v_exp_f32_e32 v54, v62
	v_add_f32_e32 v3, v51, v3
	v_exp_f32_e32 v55, v63
	v_add_f32_e32 v3, v52, v3
	v_add_f32_e32 v3, v53, v3
	v_add_f32_e32 v3, v54, v3
	v_cvt_pk_bf16_f32 v11, v5, v9
	v_add_u32_e32 v9, s36, v98
	v_add_f32_e32 v56, v55, v3
	v_cvt_pk_bf16_f32 v10, v2, v4
	v_cvt_pk_bf16_f32 v2, v48, v49
	v_cvt_pk_bf16_f32 v3, v50, v51
	v_add_u32_e32 v164, s36, v99
	ds_read_b64_tr_b16 v[148:149], v9 offset:9216
	ds_read_b64_tr_b16 v[150:151], v9 offset:10752
	ds_read_b64_tr_b16 v[152:153], v9 offset:9280
	ds_read_b64_tr_b16 v[154:155], v9 offset:10816
	ds_read_b64_tr_b16 v[156:157], v164 offset:9216
	ds_read_b64_tr_b16 v[158:159], v164 offset:10752
	ds_read_b64_tr_b16 v[160:161], v164 offset:9280
	ds_read_b64_tr_b16 v[162:163], v164 offset:10816
	v_cvt_pk_bf16_f32 v12, v12, v13
	v_cvt_pk_bf16_f32 v13, v14, v15
	v_cvt_pk_bf16_f32 v4, v52, v53
	v_cvt_pk_bf16_f32 v5, v54, v55
	v_add_f32_e32 v0, v0, v56
	s_waitcnt lgkmcnt(6)
	v_mfma_f32_32x32x16_bf16 v[32:47], v[148:151], v[10:13], v[32:47]
	s_waitcnt lgkmcnt(4)
	v_mfma_f32_32x32x16_bf16 v[16:31], v[152:155], v[10:13], v[16:31]
	s_waitcnt lgkmcnt(2)
	v_mfma_f32_32x32x16_bf16 v[32:47], v[156:159], v[2:5], v[32:47]
	s_waitcnt lgkmcnt(0)
	v_mfma_f32_32x32x16_bf16 v[16:31], v[160:163], v[2:5], v[16:31]
	s_sub_i32 s24, s33, 63
	s_cmp_gt_i32 s24, s31
	s_cbranch_scc1 .LBB0_234
; #define LAS __attribute__((address_space(3)))
; template <int MODE>
; __device__ __forceinline__ void attn_item(const AttnP& p, int b, int h, int qb, LAS unsigned char* lds) {
;     ...
;                     if (MODE == 0) {
;                         const LAS float* tab = (const LAS float*)(lds + TAB_OFF);
;                         if (qw - (kp0 + 31) >= 128) {
;                             const float cb = tab[255] - mfix;
; #pragma unroll
;                             for (int c = 0; c < NC; ++c) { ATT_QK(c, cb); ATT_TAIL(c); }
;                         } else {
;                             float binit[16];
; #pragma unroll
;                             for (int i = 0; i < 16; ++i) {
;                                 const int dist = qrow - (kp0 + crow(i, hh));
;                                 binit[i] = (dist < 0) ? -3e38f : (tab[dist > 255 ? 255 : dist] - mfix);
;                             }
; #pragma unroll
;                             for (int c = 0; c < NC; ++c) { ATT_QK(c, binit[i]); ATT_TAIL(c); }
;                         }
;                     } else {
;                         float binit[16];
;                         const LAS float* bl = (const LAS float*)(vtb + VT_BYTES) + 32 * kb2 + 4 * hh;
; #pragma unroll
;                         for (int g = 0; g < 4; ++g) {
;                             const f32x4 t = *(const LAS f32x4*)(bl + 8 * g);
; #pragma unroll
;                             for (int e = 0; e < 4; ++e) binit[4 * g + e] = (need_mask && (kp0 + crow(4 * g + e, hh) > qrow)) ? -3e38f : (t[e] - mfix);
;                         }
;                         ATT_QK(0, binit[i]); ATT_TAIL(0);
;                     }
;     ...
;                 }
; #pragma unroll
;                 for (int t2 = 0; t2 < 2; ++t2)
; #pragma unroll
;                     for (int d = 0; d < DV / 32; ++d) {
;                         const LAS unsigned char* vp = vtb + ((32 * kb2 + 16 * t2 + 4 * hh + ((lane & 15) >> 2)) * VPT + d * 32 + 16 * ((lane >> 4) & 1) + 4 * (lane & 3)) * 2;
;                         const s16x4 lo = vtr(vp), hi = vtr(vp + 8 * VPT * 2);
;                         const bf16x8 va = __builtin_shufflevector(lo, hi, 0, 1, 2, 3, 4, 5, 6, 7);
; #pragma unroll
;                         for (int c = 0; c < NC; ++c) O[c][d] = MFMA32(va, pb[c][t2], O[c][d]);
;                     }
.LBB0_236:
	ds_read_b128 v[2:5], v8 offset:21504
	ds_read_b128 v[10:13], v8 offset:21536
	s_sub_i32 s24, s33, 32
	s_cmp_gt_i32 s24, s27
	v_subrev_u32_e32 v9, 63, v7
	s_cselect_b64 s[24:25], -1, 0
	v_cmp_gt_i32_e32 vcc, v9, v115
	s_and_b64 vcc, s[24:25], vcc
	s_waitcnt lgkmcnt(0)
	v_sub_f32_e32 v2, v2, v121
	v_cndmask_b32_e32 v48, v2, v219, vcc
	v_cmp_ge_i32_e32 vcc, v9, v115
	s_and_b64 vcc, s[24:25], vcc
	v_sub_f32_e32 v2, v3, v121
	v_cndmask_b32_e32 v49, v2, v219, vcc
	v_subrev_u32_e32 v2, 61, v7
	v_cmp_gt_i32_e32 vcc, v2, v115
	s_and_b64 vcc, s[24:25], vcc
	v_sub_f32_e32 v2, v4, v121
	v_cndmask_b32_e32 v50, v2, v219, vcc
	v_subrev_u32_e32 v2, 60, v7
	v_cmp_gt_i32_e32 vcc, v2, v115
	s_and_b64 vcc, s[24:25], vcc
	v_sub_f32_e32 v2, v5, v121
	v_cndmask_b32_e32 v51, v2, v219, vcc
	v_subrev_u32_e32 v2, 55, v7
	v_cmp_gt_i32_e32 vcc, v2, v115
	s_and_b64 vcc, s[24:25], vcc
	v_sub_f32_e32 v2, v10, v121
	v_cndmask_b32_e32 v52, v2, v219, vcc
	v_subrev_u32_e32 v2, 54, v7
	v_cmp_gt_i32_e32 vcc, v2, v115
	s_and_b64 vcc, s[24:25], vcc
	v_sub_f32_e32 v2, v11, v121
	v_cndmask_b32_e32 v53, v2, v219, vcc
	v_subrev_u32_e32 v2, 53, v7
	v_cmp_gt_i32_e32 vcc, v2, v115
	s_and_b64 vcc, s[24:25], vcc
	v_sub_f32_e32 v2, v12, v121
	v_cndmask_b32_e32 v54, v2, v219, vcc
	v_subrev_u32_e32 v2, 52, v7
	v_cmp_gt_i32_e32 vcc, v2, v115
	s_and_b64 vcc, s[24:25], vcc
	v_sub_f32_e32 v2, v13, v121
	v_cndmask_b32_e32 v55, v2, v219, vcc
	ds_read_b128 v[2:5], v8 offset:21568
	v_subrev_u32_e32 v9, 47, v7
	v_cmp_gt_i32_e32 vcc, v9, v115
	s_and_b64 vcc, s[24:25], vcc
	s_waitcnt lgkmcnt(0)
	v_sub_f32_e32 v2, v2, v121
	v_cndmask_b32_e32 v56, v2, v219, vcc
	v_subrev_u32_e32 v2, 46, v7
	v_cmp_gt_i32_e32 vcc, v2, v115
	s_and_b64 vcc, s[24:25], vcc
	v_sub_f32_e32 v2, v3, v121
	v_cndmask_b32_e32 v57, v2, v219, vcc
	v_subrev_u32_e32 v2, 45, v7
	v_cmp_gt_i32_e32 vcc, v2, v115
	s_and_b64 vcc, s[24:25], vcc
	v_sub_f32_e32 v2, v4, v121
	v_cndmask_b32_e32 v58, v2, v219, vcc
	v_subrev_u32_e32 v2, 44, v7
	v_cmp_gt_i32_e32 vcc, v2, v115
	s_and_b64 vcc, s[24:25], vcc
	v_sub_f32_e32 v2, v5, v121
	v_cndmask_b32_e32 v59, v2, v219, vcc
	ds_read_b128 v[2:5], v8 offset:21600
	v_subrev_u32_e32 v8, 39, v7
	v_cmp_gt_i32_e32 vcc, v8, v115
	s_and_b64 vcc, s[24:25], vcc
	s_waitcnt lgkmcnt(0)
	v_sub_f32_e32 v2, v2, v121
	v_cndmask_b32_e32 v60, v2, v219, vcc
	v_subrev_u32_e32 v2, 38, v7
	v_cmp_gt_i32_e32 vcc, v2, v115
	s_and_b64 vcc, s[24:25], vcc
	v_sub_f32_e32 v2, v3, v121
	v_cndmask_b32_e32 v61, v2, v219, vcc
	v_subrev_u32_e32 v2, 37, v7
	v_cmp_gt_i32_e32 vcc, v2, v115
	s_and_b64 vcc, s[24:25], vcc
	v_sub_f32_e32 v2, v4, v121
	v_cndmask_b32_e32 v62, v2, v219, vcc
	v_subrev_u32_e32 v2, 36, v7
	v_cmp_gt_i32_e32 vcc, v2, v115
	s_and_b64 vcc, s[24:25], vcc
	v_sub_f32_e32 v2, v5, v121
	v_cndmask_b32_e32 v63, v2, v219, vcc
	ds_read_b128 v[2:5], v6
	ds_read_b128 v[8:11], v6 offset:32
	ds_read_b128 v[140:143], v6 offset:64
	ds_read_b128 v[144:147], v6 offset:96
	s_waitcnt lgkmcnt(3)
	v_mfma_f32_32x32x16_bf16 v[48:63], v[2:5], v[72:75], v[48:63]
	s_waitcnt lgkmcnt(2)
	v_mfma_f32_32x32x16_bf16 v[48:63], v[8:11], v[76:79], v[48:63]
	s_waitcnt lgkmcnt(1)
	v_mfma_f32_32x32x16_bf16 v[48:63], v[140:143], v[80:83], v[48:63]
	s_waitcnt lgkmcnt(0)
	v_mfma_f32_32x32x16_bf16 v[48:63], v[144:147], v[84:87], v[48:63]
	s_nop 11
	v_exp_f32_e32 v2, v48
	v_exp_f32_e32 v4, v49
	v_exp_f32_e32 v5, v50
	v_exp_f32_e32 v7, v51
	v_add_f32_e32 v3, 0, v2
	v_exp_f32_e32 v8, v52
	v_add_f32_e32 v3, v4, v3
	v_exp_f32_e32 v9, v53
	v_add_f32_e32 v3, v5, v3
	v_exp_f32_e32 v10, v54
	v_add_f32_e32 v3, v7, v3
	v_exp_f32_e32 v11, v55
	v_add_f32_e32 v3, v8, v3
	v_exp_f32_e32 v12, v56
	v_add_f32_e32 v3, v9, v3
	v_exp_f32_e32 v13, v57
	v_add_f32_e32 v3, v10, v3
	v_exp_f32_e32 v14, v58
	v_add_f32_e32 v3, v11, v3
	v_exp_f32_e32 v15, v59
	v_add_f32_e32 v3, v12, v3
	v_exp_f32_e32 v48, v60
	v_add_f32_e32 v3, v13, v3
	v_exp_f32_e32 v49, v61
	v_add_f32_e32 v3, v14, v3
	v_exp_f32_e32 v50, v62
	v_add_f32_e32 v3, v15, v3
	v_exp_f32_e32 v51, v63
	v_add_f32_e32 v3, v48, v3
	v_add_f32_e32 v3, v49, v3
	v_add_f32_e32 v3, v50, v3
	v_add_f32_e32 v52, v51, v3
	v_cvt_pk_bf16_f32 v3, v14, v15
	v_add_u32_e32 v14, s36, v97
	v_cvt_pk_bf16_f32 v6, v2, v4
	v_cvt_pk_bf16_f32 v8, v8, v9
	v_cvt_pk_bf16_f32 v9, v10, v11
	v_cvt_pk_bf16_f32 v2, v12, v13
	v_add_u32_e32 v164, s36, v100
	ds_read_b64_tr_b16 v[148:149], v14 offset:9216
	ds_read_b64_tr_b16 v[150:151], v14 offset:10752
	ds_read_b64_tr_b16 v[152:153], v14 offset:9280
	ds_read_b64_tr_b16 v[154:155], v14 offset:10816
	ds_read_b64_tr_b16 v[156:157], v164 offset:9216
	ds_read_b64_tr_b16 v[158:159], v164 offset:10752
	ds_read_b64_tr_b16 v[160:161], v164 offset:9280
	ds_read_b64_tr_b16 v[162:163], v164 offset:10816
	v_cvt_pk_bf16_f32 v7, v5, v7
	v_cvt_pk_bf16_f32 v4, v48, v49
	v_cvt_pk_bf16_f32 v5, v50, v51
	v_add_f32_e32 v0, v0, v52
	s_waitcnt lgkmcnt(6)
	v_mfma_f32_32x32x16_bf16 v[32:47], v[148:151], v[6:9], v[32:47]
	s_waitcnt lgkmcnt(4)
	v_mfma_f32_32x32x16_bf16 v[16:31], v[152:155], v[6:9], v[16:31]
	s_waitcnt lgkmcnt(2)
	v_mfma_f32_32x32x16_bf16 v[32:47], v[156:159], v[2:5], v[32:47]
	s_waitcnt lgkmcnt(0)
	v_mfma_f32_32x32x16_bf16 v[16:31], v[160:163], v[2:5], v[16:31]
	s_andn2_b64 vcc, exec, s[22:23]
	s_cbranch_vccnz .LBB0_227
